# branch-GEMM epilogue: all 16 merge-gate loads issued up-front with counted vmcnt, multiply in place (plus the out-GEMM epilogue pipeline of v1)
# speedup vs baseline: 1.0176x; 1.0176x over previous
; __device__ __forceinline__ float bflo(unsigned w) { return __uint_as_float(w << 16); }
; __device__ __forceinline__ float bfhi(unsigned w) { return __uint_as_float(w & 0xffff0000u); }
;     __device__ __forceinline__ void operator()(f32x4 (&acc)[2][2][4][2], const Unit& u, int wr, int wc, int fr, int fq) const {
;         const int br = u.pm >> 6; const int row0 = (u.pm & 63) * BM + wr * 64 + fr, col0 = (u.pn & 7) * BM + wc * 32 + 8 * fq;
; #pragma unroll
;         for (int ai = 0; ai < 2; ++ai)
; #pragma unroll
;             for (int m = 0; m < 4; ++m) { const size_t row = (size_t)(row0 + ai * HALF + m * 16);
; #pragma unroll
;                 for (int bj = 0; bj < 2; ++bj) { const int col = col0 + bj * HALF;
;                     const u32x4 gt = *(const u32x4*)(HG + row * HGW + br * 2048 + col);
;                     f32x4 v0 = acc[ai][bj][m][0], v1 = acc[ai][bj][m][1];
;                     v0[0] *= bflo(gt.x); v0[1] *= bfhi(gt.x); v0[2] *= bflo(gt.y); v0[3] *= bfhi(gt.y);
;                     v1[0] *= bflo(gt.z); v1[1] *= bfhi(gt.z); v1[2] *= bflo(gt.w); v1[3] *= bfhi(gt.w);
.LBB0_705:
	s_lshl_b32 s45, s66, 8
	s_and_b32 s45, s45, 0x3f00
	v_add_u32_e32 v2, s45, v164
	s_ashr_i32 s44, s66, 6
	s_lshl_b32 s45, s70, 8
	s_and_b32 s45, s45, 0x700
	v_or_b32_e32 v0, s45, v174
	v_lshlrev_b32_e32 v0, 1, v0
	s_lshl_b32 s45, s44, 12
	v_lshl_add_u32 v3, v2, 14, v0
	v_add_u32_e32 v3, s45, v3
	global_load_dwordx4 v[132:135], v3, s[36:37]
	global_load_dwordx4 v[136:139], v3, s[36:37] offset:256
	v_add_u32_e32 v236, 0x40000, v3
	global_load_dwordx4 v[160:163], v236, s[36:37]
	global_load_dwordx4 v[176:179], v236, s[36:37] offset:256
	v_add_u32_e32 v236, 0x80000, v3
	global_load_dwordx4 v[180:183], v236, s[36:37]
	global_load_dwordx4 v[184:187], v236, s[36:37] offset:256
	v_add_u32_e32 v236, 0xc0000, v3
	global_load_dwordx4 v[188:191], v236, s[36:37]
	global_load_dwordx4 v[192:195], v236, s[36:37] offset:256
	v_add_u32_e32 v236, 0x200000, v3
	global_load_dwordx4 v[196:199], v236, s[36:37]
	global_load_dwordx4 v[200:203], v236, s[36:37] offset:256
	v_add_u32_e32 v236, 0x240000, v3
	global_load_dwordx4 v[204:207], v236, s[36:37]
	global_load_dwordx4 v[208:211], v236, s[36:37] offset:256
	v_add_u32_e32 v236, 0x280000, v3
	global_load_dwordx4 v[212:215], v236, s[36:37]
	global_load_dwordx4 v[216:219], v236, s[36:37] offset:256
	v_add_u32_e32 v236, 0x2c0000, v3
	global_load_dwordx4 v[220:223], v236, s[36:37]
	global_load_dwordx4 v[224:227], v236, s[36:37] offset:256
	s_and_b64 vcc, exec, s[48:49]
	s_cbranch_vccz .LBB0_707
	s_barrier
.LBB0_707:
	s_waitcnt vmcnt(15)
	v_lshlrev_b32_e32 v228, 16, v132
	v_and_b32_e32 v229, 0xffff0000, v132
	v_lshlrev_b32_e32 v230, 16, v133
	v_and_b32_e32 v231, 0xffff0000, v133
	v_lshlrev_b32_e32 v232, 16, v134
	v_and_b32_e32 v233, 0xffff0000, v134
	v_lshlrev_b32_e32 v234, 16, v135
	v_and_b32_e32 v235, 0xffff0000, v135
	v_pk_mul_f32 v[128:129], v[128:129], v[228:229]
	v_pk_mul_f32 v[130:131], v[130:131], v[230:231]
	v_pk_mul_f32 v[124:125], v[124:125], v[232:233]
	v_pk_mul_f32 v[126:127], v[126:127], v[234:235]
	s_waitcnt vmcnt(14)
	v_lshlrev_b32_e32 v228, 16, v136
	v_and_b32_e32 v229, 0xffff0000, v136
	v_lshlrev_b32_e32 v230, 16, v137
	v_and_b32_e32 v231, 0xffff0000, v137
	v_lshlrev_b32_e32 v232, 16, v138
	v_and_b32_e32 v233, 0xffff0000, v138
	v_lshlrev_b32_e32 v234, 16, v139
	v_and_b32_e32 v235, 0xffff0000, v139
	v_pk_mul_f32 v[96:97], v[96:97], v[228:229]
	v_pk_mul_f32 v[98:99], v[98:99], v[230:231]
	v_pk_mul_f32 v[92:93], v[92:93], v[232:233]
	v_pk_mul_f32 v[94:95], v[94:95], v[234:235]
	s_waitcnt vmcnt(13)
	v_lshlrev_b32_e32 v228, 16, v160
	v_and_b32_e32 v229, 0xffff0000, v160
	v_lshlrev_b32_e32 v230, 16, v161
	v_and_b32_e32 v231, 0xffff0000, v161
	v_lshlrev_b32_e32 v232, 16, v162
	v_and_b32_e32 v233, 0xffff0000, v162
	v_lshlrev_b32_e32 v234, 16, v163
	v_and_b32_e32 v235, 0xffff0000, v163
	v_pk_mul_f32 v[120:121], v[120:121], v[228:229]
	v_pk_mul_f32 v[122:123], v[122:123], v[230:231]
	v_pk_mul_f32 v[116:117], v[116:117], v[232:233]
	v_pk_mul_f32 v[118:119], v[118:119], v[234:235]
	s_waitcnt vmcnt(12)
	v_lshlrev_b32_e32 v228, 16, v176
	v_and_b32_e32 v229, 0xffff0000, v176
	v_lshlrev_b32_e32 v230, 16, v177
	v_and_b32_e32 v231, 0xffff0000, v177
	v_lshlrev_b32_e32 v232, 16, v178
	v_and_b32_e32 v233, 0xffff0000, v178
	v_lshlrev_b32_e32 v234, 16, v179
	v_and_b32_e32 v235, 0xffff0000, v179
	v_pk_mul_f32 v[88:89], v[88:89], v[228:229]
	v_pk_mul_f32 v[90:91], v[90:91], v[230:231]
	v_pk_mul_f32 v[84:85], v[84:85], v[232:233]
	v_pk_mul_f32 v[86:87], v[86:87], v[234:235]
	s_waitcnt vmcnt(11)
	v_lshlrev_b32_e32 v228, 16, v180
	v_and_b32_e32 v229, 0xffff0000, v180
	v_lshlrev_b32_e32 v230, 16, v181
	v_and_b32_e32 v231, 0xffff0000, v181
	v_lshlrev_b32_e32 v232, 16, v182
	v_and_b32_e32 v233, 0xffff0000, v182
	v_lshlrev_b32_e32 v234, 16, v183
	v_and_b32_e32 v235, 0xffff0000, v183
	v_pk_mul_f32 v[112:113], v[112:113], v[228:229]
	v_pk_mul_f32 v[114:115], v[114:115], v[230:231]
	v_pk_mul_f32 v[108:109], v[108:109], v[232:233]
	v_pk_mul_f32 v[110:111], v[110:111], v[234:235]
	s_waitcnt vmcnt(10)
	v_lshlrev_b32_e32 v228, 16, v184
	v_and_b32_e32 v229, 0xffff0000, v184
	v_lshlrev_b32_e32 v230, 16, v185
	v_and_b32_e32 v231, 0xffff0000, v185
	v_lshlrev_b32_e32 v232, 16, v186
	v_and_b32_e32 v233, 0xffff0000, v186
	v_lshlrev_b32_e32 v234, 16, v187
	v_and_b32_e32 v235, 0xffff0000, v187
	v_pk_mul_f32 v[80:81], v[80:81], v[228:229]
	v_pk_mul_f32 v[82:83], v[82:83], v[230:231]
	v_pk_mul_f32 v[76:77], v[76:77], v[232:233]
	v_pk_mul_f32 v[78:79], v[78:79], v[234:235]
	s_waitcnt vmcnt(9)
	v_lshlrev_b32_e32 v228, 16, v188
	v_and_b32_e32 v229, 0xffff0000, v188
	v_lshlrev_b32_e32 v230, 16, v189
	v_and_b32_e32 v231, 0xffff0000, v189
	v_lshlrev_b32_e32 v232, 16, v190
	v_and_b32_e32 v233, 0xffff0000, v190
	v_lshlrev_b32_e32 v234, 16, v191
	v_and_b32_e32 v235, 0xffff0000, v191
	v_pk_mul_f32 v[104:105], v[104:105], v[228:229]
	v_pk_mul_f32 v[106:107], v[106:107], v[230:231]
	v_pk_mul_f32 v[100:101], v[100:101], v[232:233]
	v_pk_mul_f32 v[102:103], v[102:103], v[234:235]
	s_waitcnt vmcnt(8)
	v_lshlrev_b32_e32 v228, 16, v192
	v_and_b32_e32 v229, 0xffff0000, v192
	v_lshlrev_b32_e32 v230, 16, v193
	v_and_b32_e32 v231, 0xffff0000, v193
	v_lshlrev_b32_e32 v232, 16, v194
	v_and_b32_e32 v233, 0xffff0000, v194
	v_lshlrev_b32_e32 v234, 16, v195
	v_and_b32_e32 v235, 0xffff0000, v195
	v_pk_mul_f32 v[72:73], v[72:73], v[228:229]
	v_pk_mul_f32 v[74:75], v[74:75], v[230:231]
	v_pk_mul_f32 v[68:69], v[68:69], v[232:233]
	v_pk_mul_f32 v[70:71], v[70:71], v[234:235]
	s_waitcnt vmcnt(7)
; __device__ __forceinline__ float bflo(unsigned w) { return __uint_as_float(w << 16); }
; __device__ __forceinline__ float bfhi(unsigned w) { return __uint_as_float(w & 0xffff0000u); }
;     __device__ __forceinline__ void operator()(f32x4 (&acc)[2][2][4][2], const Unit& u, int wr, int wc, int fr, int fq) const {
;     ...
;                     f32x4 v0 = acc[ai][bj][m][0], v1 = acc[ai][bj][m][1];
;                     v0[0] *= bflo(gt.x); v0[1] *= bfhi(gt.x); v0[2] *= bflo(gt.y); v0[3] *= bfhi(gt.y);
;                     v1[0] *= bflo(gt.z); v1[1] *= bfhi(gt.z); v1[2] *= bflo(gt.w); v1[3] *= bfhi(gt.w);
;                     if (br < 3) { acc[ai][bj][m][0] = v0; acc[ai][bj][m][1] = v1; }
;                     else { u32x4 w; w.x = pk2(v0[0], v0[1]); w.y = pk2(v0[2], v0[3]); w.z = pk2(v1[0], v1[1]); w.w = pk2(v1[2], v1[3]); *(u32x4*)(MG + row * DM + col) = w; } } }
	v_lshlrev_b32_e32 v228, 16, v196
	v_and_b32_e32 v229, 0xffff0000, v196
	v_lshlrev_b32_e32 v230, 16, v197
	v_and_b32_e32 v231, 0xffff0000, v197
	v_lshlrev_b32_e32 v232, 16, v198
	v_and_b32_e32 v233, 0xffff0000, v198
	v_lshlrev_b32_e32 v234, 16, v199
	v_and_b32_e32 v235, 0xffff0000, v199
	v_pk_mul_f32 v[64:65], v[64:65], v[228:229]
	v_pk_mul_f32 v[66:67], v[66:67], v[230:231]
	v_pk_mul_f32 v[60:61], v[60:61], v[232:233]
	v_pk_mul_f32 v[62:63], v[62:63], v[234:235]
	s_waitcnt vmcnt(6)
	v_lshlrev_b32_e32 v228, 16, v200
	v_and_b32_e32 v229, 0xffff0000, v200
	v_lshlrev_b32_e32 v230, 16, v201
	v_and_b32_e32 v231, 0xffff0000, v201
	v_lshlrev_b32_e32 v232, 16, v202
	v_and_b32_e32 v233, 0xffff0000, v202
	v_lshlrev_b32_e32 v234, 16, v203
	v_and_b32_e32 v235, 0xffff0000, v203
	v_pk_mul_f32 v[32:33], v[32:33], v[228:229]
	v_pk_mul_f32 v[34:35], v[34:35], v[230:231]
	v_pk_mul_f32 v[28:29], v[28:29], v[232:233]
	v_pk_mul_f32 v[30:31], v[30:31], v[234:235]
	s_waitcnt vmcnt(5)
	v_lshlrev_b32_e32 v228, 16, v204
	v_and_b32_e32 v229, 0xffff0000, v204
	v_lshlrev_b32_e32 v230, 16, v205
	v_and_b32_e32 v231, 0xffff0000, v205
	v_lshlrev_b32_e32 v232, 16, v206
	v_and_b32_e32 v233, 0xffff0000, v206
	v_lshlrev_b32_e32 v234, 16, v207
	v_and_b32_e32 v235, 0xffff0000, v207
	v_pk_mul_f32 v[56:57], v[56:57], v[228:229]
	v_pk_mul_f32 v[58:59], v[58:59], v[230:231]
	v_pk_mul_f32 v[52:53], v[52:53], v[232:233]
	v_pk_mul_f32 v[54:55], v[54:55], v[234:235]
	s_waitcnt vmcnt(4)
	v_lshlrev_b32_e32 v228, 16, v208
	v_and_b32_e32 v229, 0xffff0000, v208
	v_lshlrev_b32_e32 v230, 16, v209
	v_and_b32_e32 v231, 0xffff0000, v209
	v_lshlrev_b32_e32 v232, 16, v210
	v_and_b32_e32 v233, 0xffff0000, v210
	v_lshlrev_b32_e32 v234, 16, v211
	v_and_b32_e32 v235, 0xffff0000, v211
	v_pk_mul_f32 v[24:25], v[24:25], v[228:229]
	v_pk_mul_f32 v[26:27], v[26:27], v[230:231]
	v_pk_mul_f32 v[20:21], v[20:21], v[232:233]
	v_pk_mul_f32 v[22:23], v[22:23], v[234:235]
	s_waitcnt vmcnt(3)
	v_lshlrev_b32_e32 v228, 16, v212
	v_and_b32_e32 v229, 0xffff0000, v212
	v_lshlrev_b32_e32 v230, 16, v213
	v_and_b32_e32 v231, 0xffff0000, v213
	v_lshlrev_b32_e32 v232, 16, v214
	v_and_b32_e32 v233, 0xffff0000, v214
	v_lshlrev_b32_e32 v234, 16, v215
	v_and_b32_e32 v235, 0xffff0000, v215
	v_pk_mul_f32 v[48:49], v[48:49], v[228:229]
	v_pk_mul_f32 v[50:51], v[50:51], v[230:231]
	v_pk_mul_f32 v[44:45], v[44:45], v[232:233]
	v_pk_mul_f32 v[46:47], v[46:47], v[234:235]
	s_waitcnt vmcnt(2)
	v_lshlrev_b32_e32 v228, 16, v216
	v_and_b32_e32 v229, 0xffff0000, v216
	v_lshlrev_b32_e32 v230, 16, v217
	v_and_b32_e32 v231, 0xffff0000, v217
	v_lshlrev_b32_e32 v232, 16, v218
	v_and_b32_e32 v233, 0xffff0000, v218
	v_lshlrev_b32_e32 v234, 16, v219
	v_and_b32_e32 v235, 0xffff0000, v219
	v_pk_mul_f32 v[16:17], v[16:17], v[228:229]
	v_pk_mul_f32 v[18:19], v[18:19], v[230:231]
	v_pk_mul_f32 v[12:13], v[12:13], v[232:233]
	v_pk_mul_f32 v[14:15], v[14:15], v[234:235]
	s_waitcnt vmcnt(1)
	v_lshlrev_b32_e32 v228, 16, v220
	v_and_b32_e32 v229, 0xffff0000, v220
	v_lshlrev_b32_e32 v230, 16, v221
	v_and_b32_e32 v231, 0xffff0000, v221
	v_lshlrev_b32_e32 v232, 16, v222
	v_and_b32_e32 v233, 0xffff0000, v222
	v_lshlrev_b32_e32 v234, 16, v223
	v_and_b32_e32 v235, 0xffff0000, v223
	v_pk_mul_f32 v[40:41], v[40:41], v[228:229]
	v_pk_mul_f32 v[42:43], v[42:43], v[230:231]
	v_pk_mul_f32 v[36:37], v[36:37], v[232:233]
	v_pk_mul_f32 v[38:39], v[38:39], v[234:235]
	s_waitcnt vmcnt(0)
	v_lshlrev_b32_e32 v228, 16, v224
	v_and_b32_e32 v229, 0xffff0000, v224
	v_lshlrev_b32_e32 v230, 16, v225
	v_and_b32_e32 v231, 0xffff0000, v225
	v_lshlrev_b32_e32 v232, 16, v226
	v_and_b32_e32 v233, 0xffff0000, v226
	v_lshlrev_b32_e32 v234, 16, v227
	v_and_b32_e32 v235, 0xffff0000, v227
	v_pk_mul_f32 v[8:9], v[8:9], v[228:229]
	v_pk_mul_f32 v[10:11], v[10:11], v[230:231]
	v_pk_mul_f32 v[4:5], v[4:5], v[232:233]
	v_pk_mul_f32 v[6:7], v[6:7], v[234:235]
	s_cmp_gt_i32 s44, 2
	s_cbranch_scc0 .Lbr_keep_acc
;     __device__ __forceinline__ void operator()(f32x4 (&acc)[2][2][4][2], const Unit& u, int wr, int wc, int fr, int fq) const {
;     ...
;                     if (br < 3) { acc[ai][bj][m][0] = v0; acc[ai][bj][m][1] = v1; }
;                     else { u32x4 w; w.x = pk2(v0[0], v0[1]); w.y = pk2(v0[2], v0[3]); w.z = pk2(v1[0], v1[1]); w.w = pk2(v1[2], v1[3]); *(u32x4*)(MG + row * DM + col) = w; } } }
	v_lshl_add_u32 v2, v2, 12, v0
	v_cvt_pk_bf16_f32 v132, v128, v129
	v_cvt_pk_bf16_f32 v133, v130, v131
	v_cvt_pk_bf16_f32 v134, v124, v125
	v_cvt_pk_bf16_f32 v135, v126, v127
	global_store_dwordx4 v2, v[132:135], s[38:39]
	v_cvt_pk_bf16_f32 v136, v96, v97
	v_cvt_pk_bf16_f32 v137, v98, v99
	v_cvt_pk_bf16_f32 v138, v92, v93
	v_cvt_pk_bf16_f32 v139, v94, v95
	global_store_dwordx4 v2, v[136:139], s[38:39] offset:256
	v_add_u32_e32 v237, 0x10000, v2
	v_cvt_pk_bf16_f32 v160, v120, v121
	v_cvt_pk_bf16_f32 v161, v122, v123
	v_cvt_pk_bf16_f32 v162, v116, v117
	v_cvt_pk_bf16_f32 v163, v118, v119
	global_store_dwordx4 v237, v[160:163], s[38:39]
	v_cvt_pk_bf16_f32 v176, v88, v89
	v_cvt_pk_bf16_f32 v177, v90, v91
	v_cvt_pk_bf16_f32 v178, v84, v85
	v_cvt_pk_bf16_f32 v179, v86, v87
	global_store_dwordx4 v237, v[176:179], s[38:39] offset:256
	v_add_u32_e32 v237, 0x20000, v2
	v_cvt_pk_bf16_f32 v180, v112, v113
	v_cvt_pk_bf16_f32 v181, v114, v115
	v_cvt_pk_bf16_f32 v182, v108, v109
	v_cvt_pk_bf16_f32 v183, v110, v111
	global_store_dwordx4 v237, v[180:183], s[38:39]
	v_cvt_pk_bf16_f32 v184, v80, v81
	v_cvt_pk_bf16_f32 v185, v82, v83
	v_cvt_pk_bf16_f32 v186, v76, v77
	v_cvt_pk_bf16_f32 v187, v78, v79
	global_store_dwordx4 v237, v[184:187], s[38:39] offset:256
	v_add_u32_e32 v237, 0x30000, v2
	v_cvt_pk_bf16_f32 v188, v104, v105
	v_cvt_pk_bf16_f32 v189, v106, v107
	v_cvt_pk_bf16_f32 v190, v100, v101
	v_cvt_pk_bf16_f32 v191, v102, v103
	global_store_dwordx4 v237, v[188:191], s[38:39]
	v_cvt_pk_bf16_f32 v192, v72, v73
	v_cvt_pk_bf16_f32 v193, v74, v75
	v_cvt_pk_bf16_f32 v194, v68, v69
	v_cvt_pk_bf16_f32 v195, v70, v71
	global_store_dwordx4 v237, v[192:195], s[38:39] offset:256
	v_add_u32_e32 v237, 0x80000, v2
	v_cvt_pk_bf16_f32 v196, v64, v65
	v_cvt_pk_bf16_f32 v197, v66, v67
	v_cvt_pk_bf16_f32 v198, v60, v61
	v_cvt_pk_bf16_f32 v199, v62, v63
	global_store_dwordx4 v237, v[196:199], s[38:39]
	v_cvt_pk_bf16_f32 v200, v32, v33
	v_cvt_pk_bf16_f32 v201, v34, v35
	v_cvt_pk_bf16_f32 v202, v28, v29
	v_cvt_pk_bf16_f32 v203, v30, v31
	global_store_dwordx4 v237, v[200:203], s[38:39] offset:256
	v_add_u32_e32 v237, 0x90000, v2
	v_cvt_pk_bf16_f32 v204, v56, v57
	v_cvt_pk_bf16_f32 v205, v58, v59
	v_cvt_pk_bf16_f32 v206, v52, v53
	v_cvt_pk_bf16_f32 v207, v54, v55
	global_store_dwordx4 v237, v[204:207], s[38:39]
	v_cvt_pk_bf16_f32 v208, v24, v25
	v_cvt_pk_bf16_f32 v209, v26, v27
	v_cvt_pk_bf16_f32 v210, v20, v21
	v_cvt_pk_bf16_f32 v211, v22, v23
	global_store_dwordx4 v237, v[208:211], s[38:39] offset:256
	v_add_u32_e32 v237, 0xa0000, v2
	v_cvt_pk_bf16_f32 v212, v48, v49
	v_cvt_pk_bf16_f32 v213, v50, v51
	v_cvt_pk_bf16_f32 v214, v44, v45
	v_cvt_pk_bf16_f32 v215, v46, v47
	global_store_dwordx4 v237, v[212:215], s[38:39]
	v_cvt_pk_bf16_f32 v216, v16, v17
	v_cvt_pk_bf16_f32 v217, v18, v19
	v_cvt_pk_bf16_f32 v218, v12, v13
	v_cvt_pk_bf16_f32 v219, v14, v15
	global_store_dwordx4 v237, v[216:219], s[38:39] offset:256
	v_add_u32_e32 v237, 0xb0000, v2
	v_cvt_pk_bf16_f32 v220, v40, v41
	v_cvt_pk_bf16_f32 v221, v42, v43
	v_cvt_pk_bf16_f32 v222, v36, v37
	v_cvt_pk_bf16_f32 v223, v38, v39
	global_store_dwordx4 v237, v[220:223], s[38:39]
	v_cvt_pk_bf16_f32 v224, v8, v9
	v_cvt_pk_bf16_f32 v225, v10, v11
	v_cvt_pk_bf16_f32 v226, v4, v5
	v_cvt_pk_bf16_f32 v227, v6, v7
	global_store_dwordx4 v237, v[224:227], s[38:39] offset:256
.Lbr_keep_acc:
	s_and_b64 vcc, exec, s[42:43]
	s_mov_b64 s[42:43], -1
	s_cbranch_vccnz .LBB0_691
